# v47 + compute segments of the five GEMM K-loops: removed the 80 compiler s_waitcnt lgkmcnt(N) that can never wait (every load segment already ends with lgkmcnt(0) before its barrier)
# baseline (speedup 1.0000x reference)
.LBB0_289:
	ds_read_b128 v[134:137], v161
	ds_read_b128 v[138:141], v161 offset:1024
	ds_read_b128 v[142:145], v161 offset:2048
	ds_read_b128 v[146:149], v161 offset:3072
	ds_read_b128 v[150:153], v162
	ds_read_b128 v[166:169], v162 offset:1024
	ds_read_b128 v[170:173], v162 offset:2048
	ds_read_b128 v[174:177], v162 offset:3072
	s_add_i32 s39, s78, 0xfffc0080
	s_cmp_eq_u32 s80, 12
	s_cselect_b32 s88, s18, s39
	s_cselect_b32 s83, s19, s79
	s_or_b32 s82, s88, 0x80
	s_mov_b32 m0, s59
	ds_read_b128 v[178:181], v163
	ds_read_b128 v[182:185], v163 offset:1024
	ds_read_b128 v[186:189], v163 offset:2048
	ds_read_b128 v[190:193], v163 offset:3072
	ds_read_b128 v[194:197], v163 offset:4096
	ds_read_b128 v[198:201], v163 offset:5120
	ds_read_b128 v[202:205], v163 offset:6144
	ds_read_b128 v[206:209], v163 offset:7168
	buffer_load_dwordx4 v1, s[28:31], s78 offen lds
	s_mov_b32 m0, s60
	s_nop 0
	buffer_load_dwordx4 v155, s[28:31], s78 offen lds
	s_waitcnt vmcnt(8)
	s_waitcnt lgkmcnt(0)
	s_barrier
	s_setprio 1
	v_mfma_i32_16x16x64_i8 v[126:129], v[134:137], v[178:181], v[126:129]
	v_mfma_i32_16x16x64_i8 v[122:125], v[142:145], v[178:181], v[122:125]
	v_mfma_i32_16x16x64_i8 v[110:113], v[134:137], v[186:189], v[110:113]
	v_mfma_i32_16x16x64_i8 v[106:109], v[142:145], v[186:189], v[106:109]
	v_mfma_i32_16x16x64_i8 v[94:97], v[134:137], v[194:197], v[94:97]
	v_mfma_i32_16x16x64_i8 v[90:93], v[142:145], v[194:197], v[90:93]
	v_mfma_i32_16x16x64_i8 v[78:81], v[134:137], v[202:205], v[78:81]
	v_mfma_i32_16x16x64_i8 v[74:77], v[142:145], v[202:205], v[74:77]
	v_mfma_i32_16x16x64_i8 v[126:129], v[138:141], v[182:185], v[126:129]
	v_mfma_i32_16x16x64_i8 v[122:125], v[146:149], v[182:185], v[122:125]
	v_mfma_i32_16x16x64_i8 v[110:113], v[138:141], v[190:193], v[110:113]
	v_mfma_i32_16x16x64_i8 v[106:109], v[146:149], v[190:193], v[106:109]
	v_mfma_i32_16x16x64_i8 v[94:97], v[138:141], v[198:201], v[94:97]
	v_mfma_i32_16x16x64_i8 v[90:93], v[146:149], v[198:201], v[90:93]
	v_mfma_i32_16x16x64_i8 v[78:81], v[138:141], v[206:209], v[78:81]
	v_mfma_i32_16x16x64_i8 v[74:77], v[146:149], v[206:209], v[74:77]
	s_setprio 0
	s_setprio 1
	v_mfma_i32_16x16x64_i8 v[118:121], v[150:153], v[178:181], v[118:121]
	v_mfma_i32_16x16x64_i8 v[114:117], v[170:173], v[178:181], v[114:117]
	v_mfma_i32_16x16x64_i8 v[102:105], v[150:153], v[186:189], v[102:105]
	v_mfma_i32_16x16x64_i8 v[98:101], v[170:173], v[186:189], v[98:101]
	v_mfma_i32_16x16x64_i8 v[86:89], v[150:153], v[194:197], v[86:89]
	v_mfma_i32_16x16x64_i8 v[82:85], v[170:173], v[194:197], v[82:85]
	v_mfma_i32_16x16x64_i8 v[70:73], v[150:153], v[202:205], v[70:73]
	v_mfma_i32_16x16x64_i8 v[66:69], v[170:173], v[202:205], v[66:69]
	v_mfma_i32_16x16x64_i8 v[118:121], v[166:169], v[182:185], v[118:121]
	v_mfma_i32_16x16x64_i8 v[114:117], v[174:177], v[182:185], v[114:117]
	v_mfma_i32_16x16x64_i8 v[102:105], v[166:169], v[190:193], v[102:105]
	v_mfma_i32_16x16x64_i8 v[98:101], v[174:177], v[190:193], v[98:101]
	v_mfma_i32_16x16x64_i8 v[86:89], v[166:169], v[198:201], v[86:89]
	v_mfma_i32_16x16x64_i8 v[82:85], v[174:177], v[198:201], v[82:85]
	v_mfma_i32_16x16x64_i8 v[70:73], v[166:169], v[206:209], v[70:73]
	v_mfma_i32_16x16x64_i8 v[66:69], v[174:177], v[206:209], v[66:69]
	s_setprio 0
	s_barrier
	s_mov_b32 m0, s35
	s_mov_b32 s39, s31
	ds_read_b128 v[178:181], v163 offset:16384
	ds_read_b128 v[182:185], v163 offset:17408
	ds_read_b128 v[186:189], v163 offset:18432
	ds_read_b128 v[190:193], v163 offset:19456
	ds_read_b128 v[194:197], v163 offset:20480
	ds_read_b128 v[198:201], v163 offset:21504
	ds_read_b128 v[202:205], v163 offset:22528
	ds_read_b128 v[206:209], v163 offset:23552
	buffer_load_dwordx4 v154, s[36:39], s83 offen lds
	s_mov_b32 m0, s40
	s_add_i32 s89, s83, 0x40000
	buffer_load_dwordx4 v156, s[36:39], s83 offen lds
	s_mov_b32 m0, s41
	s_nop 0
	buffer_load_dwordx4 v154, s[36:39], s89 offen lds
	s_mov_b32 m0, s43
	s_nop 0
	buffer_load_dwordx4 v156, s[36:39], s89 offen lds
	s_mov_b32 m0, s34
	s_nop 0
	buffer_load_dwordx4 v1, s[28:31], s88 offen lds
	s_mov_b32 m0, s44
	s_nop 0
	buffer_load_dwordx4 v155, s[28:31], s88 offen lds
	s_waitcnt vmcnt(8)
	s_waitcnt lgkmcnt(0)
	s_barrier
	s_setprio 1
	v_mfma_i32_16x16x64_i8 v[62:65], v[134:137], v[178:181], v[62:65]
	v_mfma_i32_16x16x64_i8 v[58:61], v[142:145], v[178:181], v[58:61]
	v_mfma_i32_16x16x64_i8 v[46:49], v[134:137], v[186:189], v[46:49]
	v_mfma_i32_16x16x64_i8 v[42:45], v[142:145], v[186:189], v[42:45]
	v_mfma_i32_16x16x64_i8 v[30:33], v[134:137], v[194:197], v[30:33]
	v_mfma_i32_16x16x64_i8 v[26:29], v[142:145], v[194:197], v[26:29]
	v_mfma_i32_16x16x64_i8 v[14:17], v[134:137], v[202:205], v[14:17]
	v_mfma_i32_16x16x64_i8 v[10:13], v[142:145], v[202:205], v[10:13]
	v_mfma_i32_16x16x64_i8 v[62:65], v[138:141], v[182:185], v[62:65]
	v_mfma_i32_16x16x64_i8 v[58:61], v[146:149], v[182:185], v[58:61]
	v_mfma_i32_16x16x64_i8 v[46:49], v[138:141], v[190:193], v[46:49]
	v_mfma_i32_16x16x64_i8 v[42:45], v[146:149], v[190:193], v[42:45]
	v_mfma_i32_16x16x64_i8 v[30:33], v[138:141], v[198:201], v[30:33]
	v_mfma_i32_16x16x64_i8 v[26:29], v[146:149], v[198:201], v[26:29]
	v_mfma_i32_16x16x64_i8 v[14:17], v[138:141], v[206:209], v[14:17]
	v_mfma_i32_16x16x64_i8 v[10:13], v[146:149], v[206:209], v[10:13]
	s_setprio 0
	s_setprio 1
	v_mfma_i32_16x16x64_i8 v[54:57], v[150:153], v[178:181], v[54:57]
	v_mfma_i32_16x16x64_i8 v[50:53], v[170:173], v[178:181], v[50:53]
	v_mfma_i32_16x16x64_i8 v[38:41], v[150:153], v[186:189], v[38:41]
	v_mfma_i32_16x16x64_i8 v[34:37], v[170:173], v[186:189], v[34:37]
	v_mfma_i32_16x16x64_i8 v[22:25], v[150:153], v[194:197], v[22:25]
	v_mfma_i32_16x16x64_i8 v[18:21], v[170:173], v[194:197], v[18:21]
	v_mfma_i32_16x16x64_i8 v[6:9], v[150:153], v[202:205], v[6:9]
	v_mfma_i32_16x16x64_i8 v[2:5], v[170:173], v[202:205], v[2:5]
	v_mfma_i32_16x16x64_i8 v[54:57], v[166:169], v[182:185], v[54:57]
	v_mfma_i32_16x16x64_i8 v[50:53], v[174:177], v[182:185], v[50:53]
	v_mfma_i32_16x16x64_i8 v[38:41], v[166:169], v[190:193], v[38:41]
	v_mfma_i32_16x16x64_i8 v[34:37], v[174:177], v[190:193], v[34:37]
	v_mfma_i32_16x16x64_i8 v[22:25], v[166:169], v[198:201], v[22:25]
	v_mfma_i32_16x16x64_i8 v[18:21], v[174:177], v[198:201], v[18:21]
	v_mfma_i32_16x16x64_i8 v[6:9], v[166:169], v[206:209], v[6:9]
	v_mfma_i32_16x16x64_i8 v[2:5], v[174:177], v[206:209], v[2:5]
	s_setprio 0
	s_barrier
	ds_read_b128 v[134:137], v164
	ds_read_b128 v[138:141], v164 offset:1024
	ds_read_b128 v[142:145], v164 offset:2048
	ds_read_b128 v[146:149], v164 offset:3072
	ds_read_b128 v[150:153], v165
	ds_read_b128 v[166:169], v165 offset:1024
	ds_read_b128 v[170:173], v165 offset:2048
	ds_read_b128 v[174:177], v165 offset:3072
	s_add_i32 s88, s88, 0x40000
	s_mov_b32 m0, s45
	ds_read_b128 v[178:181], v163 offset:32768
	ds_read_b128 v[182:185], v163 offset:33792
	ds_read_b128 v[186:189], v163 offset:34816
	ds_read_b128 v[190:193], v163 offset:35840
	ds_read_b128 v[194:197], v163 offset:36864
	ds_read_b128 v[198:201], v163 offset:37888
	ds_read_b128 v[202:205], v163 offset:38912
	ds_read_b128 v[206:209], v163 offset:39936
	buffer_load_dwordx4 v1, s[28:31], s88 offen lds
	s_mov_b32 m0, s47
	s_nop 0
	buffer_load_dwordx4 v155, s[28:31], s88 offen lds
	s_waitcnt vmcnt(8)
	s_waitcnt lgkmcnt(0)
	s_barrier
	s_setprio 1
	v_mfma_i32_16x16x64_i8 v[126:129], v[134:137], v[178:181], v[126:129]
	v_mfma_i32_16x16x64_i8 v[122:125], v[142:145], v[178:181], v[122:125]
	v_mfma_i32_16x16x64_i8 v[110:113], v[134:137], v[186:189], v[110:113]
	v_mfma_i32_16x16x64_i8 v[106:109], v[142:145], v[186:189], v[106:109]
	v_mfma_i32_16x16x64_i8 v[94:97], v[134:137], v[194:197], v[94:97]
	v_mfma_i32_16x16x64_i8 v[90:93], v[142:145], v[194:197], v[90:93]
	v_mfma_i32_16x16x64_i8 v[78:81], v[134:137], v[202:205], v[78:81]
	v_mfma_i32_16x16x64_i8 v[74:77], v[142:145], v[202:205], v[74:77]
	v_mfma_i32_16x16x64_i8 v[126:129], v[138:141], v[182:185], v[126:129]
	v_mfma_i32_16x16x64_i8 v[122:125], v[146:149], v[182:185], v[122:125]
	v_mfma_i32_16x16x64_i8 v[110:113], v[138:141], v[190:193], v[110:113]
	v_mfma_i32_16x16x64_i8 v[106:109], v[146:149], v[190:193], v[106:109]
	v_mfma_i32_16x16x64_i8 v[94:97], v[138:141], v[198:201], v[94:97]
	v_mfma_i32_16x16x64_i8 v[90:93], v[146:149], v[198:201], v[90:93]
	v_mfma_i32_16x16x64_i8 v[78:81], v[138:141], v[206:209], v[78:81]
	v_mfma_i32_16x16x64_i8 v[74:77], v[146:149], v[206:209], v[74:77]
	s_setprio 0
	s_setprio 1
	v_mfma_i32_16x16x64_i8 v[118:121], v[150:153], v[178:181], v[118:121]
	v_mfma_i32_16x16x64_i8 v[114:117], v[170:173], v[178:181], v[114:117]
	v_mfma_i32_16x16x64_i8 v[102:105], v[150:153], v[186:189], v[102:105]
	v_mfma_i32_16x16x64_i8 v[98:101], v[170:173], v[186:189], v[98:101]
	v_mfma_i32_16x16x64_i8 v[86:89], v[150:153], v[194:197], v[86:89]
	v_mfma_i32_16x16x64_i8 v[82:85], v[170:173], v[194:197], v[82:85]
	v_mfma_i32_16x16x64_i8 v[70:73], v[150:153], v[202:205], v[70:73]
	v_mfma_i32_16x16x64_i8 v[66:69], v[170:173], v[202:205], v[66:69]
	v_mfma_i32_16x16x64_i8 v[118:121], v[166:169], v[182:185], v[118:121]
	v_mfma_i32_16x16x64_i8 v[114:117], v[174:177], v[182:185], v[114:117]
	v_mfma_i32_16x16x64_i8 v[102:105], v[166:169], v[190:193], v[102:105]
	v_mfma_i32_16x16x64_i8 v[98:101], v[174:177], v[190:193], v[98:101]
	v_mfma_i32_16x16x64_i8 v[86:89], v[166:169], v[198:201], v[86:89]
	v_mfma_i32_16x16x64_i8 v[82:85], v[174:177], v[198:201], v[82:85]
	v_mfma_i32_16x16x64_i8 v[70:73], v[166:169], v[206:209], v[70:73]
	v_mfma_i32_16x16x64_i8 v[66:69], v[174:177], v[206:209], v[66:69]
	s_setprio 0
	s_barrier
	s_mov_b32 m0, s48
	s_or_b32 s88, s83, 0x80
	ds_read_b128 v[178:181], v163 offset:49152
	ds_read_b128 v[182:185], v163 offset:50176
	ds_read_b128 v[186:189], v163 offset:51200
	ds_read_b128 v[190:193], v163 offset:52224
	ds_read_b128 v[194:197], v163 offset:53248
	ds_read_b128 v[198:201], v163 offset:54272
	ds_read_b128 v[202:205], v163 offset:55296
	ds_read_b128 v[206:209], v163 offset:56320
	buffer_load_dwordx4 v154, s[36:39], s88 offen lds
	s_mov_b32 m0, s49
	s_add_i32 s83, s83, 0x40080
	buffer_load_dwordx4 v156, s[36:39], s88 offen lds
	s_mov_b32 m0, s53
	s_nop 0
	buffer_load_dwordx4 v154, s[36:39], s83 offen lds
	s_mov_b32 m0, s55
	s_nop 0
	buffer_load_dwordx4 v156, s[36:39], s83 offen lds
	s_mov_b32 m0, s51
	s_nop 0
	buffer_load_dwordx4 v1, s[28:31], s82 offen lds
	s_mov_b32 m0, s52
	s_nop 0
	buffer_load_dwordx4 v155, s[28:31], s82 offen lds
	s_waitcnt vmcnt(8)
	s_waitcnt lgkmcnt(0)
	s_barrier
	s_setprio 1
	v_mfma_i32_16x16x64_i8 v[62:65], v[134:137], v[178:181], v[62:65]
	v_mfma_i32_16x16x64_i8 v[58:61], v[142:145], v[178:181], v[58:61]
	v_mfma_i32_16x16x64_i8 v[46:49], v[134:137], v[186:189], v[46:49]
	v_mfma_i32_16x16x64_i8 v[42:45], v[142:145], v[186:189], v[42:45]
	v_mfma_i32_16x16x64_i8 v[30:33], v[134:137], v[194:197], v[30:33]
	v_mfma_i32_16x16x64_i8 v[26:29], v[142:145], v[194:197], v[26:29]
	v_mfma_i32_16x16x64_i8 v[14:17], v[134:137], v[202:205], v[14:17]
	v_mfma_i32_16x16x64_i8 v[10:13], v[142:145], v[202:205], v[10:13]
	v_mfma_i32_16x16x64_i8 v[62:65], v[138:141], v[182:185], v[62:65]
	v_mfma_i32_16x16x64_i8 v[58:61], v[146:149], v[182:185], v[58:61]
	v_mfma_i32_16x16x64_i8 v[46:49], v[138:141], v[190:193], v[46:49]
	v_mfma_i32_16x16x64_i8 v[42:45], v[146:149], v[190:193], v[42:45]
	v_mfma_i32_16x16x64_i8 v[30:33], v[138:141], v[198:201], v[30:33]
	v_mfma_i32_16x16x64_i8 v[26:29], v[146:149], v[198:201], v[26:29]
	v_mfma_i32_16x16x64_i8 v[14:17], v[138:141], v[206:209], v[14:17]
	v_mfma_i32_16x16x64_i8 v[10:13], v[146:149], v[206:209], v[10:13]
	s_setprio 0
	s_setprio 1
	v_mfma_i32_16x16x64_i8 v[54:57], v[150:153], v[178:181], v[54:57]
	v_mfma_i32_16x16x64_i8 v[50:53], v[170:173], v[178:181], v[50:53]
	v_mfma_i32_16x16x64_i8 v[38:41], v[150:153], v[186:189], v[38:41]
	v_mfma_i32_16x16x64_i8 v[34:37], v[170:173], v[186:189], v[34:37]
	v_mfma_i32_16x16x64_i8 v[22:25], v[150:153], v[194:197], v[22:25]
	v_mfma_i32_16x16x64_i8 v[18:21], v[170:173], v[194:197], v[18:21]
	v_mfma_i32_16x16x64_i8 v[6:9], v[150:153], v[202:205], v[6:9]
	v_mfma_i32_16x16x64_i8 v[2:5], v[170:173], v[202:205], v[2:5]
	v_mfma_i32_16x16x64_i8 v[54:57], v[166:169], v[182:185], v[54:57]
	v_mfma_i32_16x16x64_i8 v[50:53], v[174:177], v[182:185], v[50:53]
	v_mfma_i32_16x16x64_i8 v[38:41], v[166:169], v[190:193], v[38:41]
	v_mfma_i32_16x16x64_i8 v[34:37], v[174:177], v[190:193], v[34:37]
	v_mfma_i32_16x16x64_i8 v[22:25], v[166:169], v[198:201], v[22:25]
	v_mfma_i32_16x16x64_i8 v[18:21], v[174:177], v[198:201], v[18:21]
	v_mfma_i32_16x16x64_i8 v[6:9], v[166:169], v[206:209], v[6:9]
	v_mfma_i32_16x16x64_i8 v[2:5], v[174:177], v[206:209], v[2:5]
	s_setprio 0
	s_barrier
	s_add_i32 s80, s80, 2
	s_addk_i32 s78, 0x100
	s_addk_i32 s79, 0x100
	s_cmp_gt_u32 s80, 13
	s_cbranch_scc0 .LBB0_289
	s_and_b64 vcc, exec, s[16:17]
	s_cbranch_vccz .LBB0_292
	s_barrier

.LBB0_366:
	ds_read_b128 v[136:139], v203
	ds_read_b128 v[140:143], v203 offset:1024
	ds_read_b128 v[144:147], v203 offset:2048
	ds_read_b128 v[148:151], v203 offset:3072
	ds_read_b128 v[152:155], v204
	ds_read_b128 v[156:159], v204 offset:1024
	ds_read_b128 v[160:163], v204 offset:2048
	ds_read_b128 v[164:167], v204 offset:3072
	s_add_i32 s39, s90, 0xffea0080
	s_cmpk_lg_i32 s89, 0x54
	s_cselect_b32 vcc_lo, s39, 0
	s_add_i32 vcc_hi, vcc_lo, s17
	s_or_b32 s91, vcc_hi, 0x80
	s_add_i32 s93, vcc_lo, s8
	s_add_i32 s39, s17, s90
	s_mov_b32 s43, s31
	s_mov_b32 m0, s80
	ds_read_b128 v[168:171], v135
	ds_read_b128 v[172:175], v135 offset:1024
	ds_read_b128 v[176:179], v135 offset:2048
	ds_read_b128 v[180:183], v135 offset:3072
	ds_read_b128 v[184:187], v135 offset:4096
	ds_read_b128 v[188:191], v135 offset:5120
	ds_read_b128 v[192:195], v135 offset:6144
	ds_read_b128 v[196:199], v135 offset:7168
	buffer_load_dwordx4 v130, s[40:43], s39 offen lds
	s_mov_b32 m0, s88
	s_nop 0
	buffer_load_dwordx4 v132, s[40:43], s39 offen lds
	s_waitcnt vmcnt(8)
	s_waitcnt lgkmcnt(0)
	s_barrier
	s_setprio 1
	v_mfma_f32_16x16x32_bf16 v[26:29], v[136:139], v[168:171], v[26:29]
	v_mfma_f32_16x16x32_bf16 v[18:21], v[144:147], v[168:171], v[18:21]
	v_mfma_f32_16x16x32_bf16 v[42:45], v[136:139], v[176:179], v[42:45]
	v_mfma_f32_16x16x32_bf16 v[34:37], v[144:147], v[176:179], v[34:37]
	v_mfma_f32_16x16x32_bf16 v[54:57], v[136:139], v[184:187], v[54:57]
	v_mfma_f32_16x16x32_bf16 v[50:53], v[144:147], v[184:187], v[50:53]
	v_mfma_f32_16x16x32_bf16 v[78:81], v[136:139], v[192:195], v[78:81]
	v_mfma_f32_16x16x32_bf16 v[70:73], v[144:147], v[192:195], v[70:73]
	v_mfma_f32_16x16x32_bf16 v[26:29], v[140:143], v[172:175], v[26:29]
	v_mfma_f32_16x16x32_bf16 v[18:21], v[148:151], v[172:175], v[18:21]
	v_mfma_f32_16x16x32_bf16 v[42:45], v[140:143], v[180:183], v[42:45]
	v_mfma_f32_16x16x32_bf16 v[34:37], v[148:151], v[180:183], v[34:37]
	v_mfma_f32_16x16x32_bf16 v[54:57], v[140:143], v[188:191], v[54:57]
	v_mfma_f32_16x16x32_bf16 v[50:53], v[148:151], v[188:191], v[50:53]
	v_mfma_f32_16x16x32_bf16 v[78:81], v[140:143], v[196:199], v[78:81]
	v_mfma_f32_16x16x32_bf16 v[70:73], v[148:151], v[196:199], v[70:73]
	s_setprio 0
	s_setprio 1
	v_mfma_f32_16x16x32_bf16 v[46:49], v[152:155], v[168:171], v[46:49]
	v_mfma_f32_16x16x32_bf16 v[38:41], v[160:163], v[168:171], v[38:41]
	v_mfma_f32_16x16x32_bf16 v[62:65], v[152:155], v[176:179], v[62:65]
	v_mfma_f32_16x16x32_bf16 v[58:61], v[160:163], v[176:179], v[58:61]
	v_mfma_f32_16x16x32_bf16 v[86:89], v[152:155], v[184:187], v[86:89]
	v_mfma_f32_16x16x32_bf16 v[82:85], v[160:163], v[184:187], v[82:85]
	v_mfma_f32_16x16x32_bf16 v[102:105], v[152:155], v[192:195], v[102:105]
	v_mfma_f32_16x16x32_bf16 v[98:101], v[160:163], v[192:195], v[98:101]
	v_mfma_f32_16x16x32_bf16 v[46:49], v[156:159], v[172:175], v[46:49]
	v_mfma_f32_16x16x32_bf16 v[38:41], v[164:167], v[172:175], v[38:41]
	v_mfma_f32_16x16x32_bf16 v[62:65], v[156:159], v[180:183], v[62:65]
	v_mfma_f32_16x16x32_bf16 v[58:61], v[164:167], v[180:183], v[58:61]
	v_mfma_f32_16x16x32_bf16 v[86:89], v[156:159], v[188:191], v[86:89]
	v_mfma_f32_16x16x32_bf16 v[82:85], v[164:167], v[188:191], v[82:85]
	v_mfma_f32_16x16x32_bf16 v[102:105], v[156:159], v[196:199], v[102:105]
	v_mfma_f32_16x16x32_bf16 v[98:101], v[164:167], v[196:199], v[98:101]
	s_setprio 0
	s_barrier
	s_mov_b32 m0, s10
	s_mov_b32 s39, s31
	ds_read_b128 v[168:171], v135 offset:16384
	ds_read_b128 v[172:175], v135 offset:17408
	ds_read_b128 v[176:179], v135 offset:18432
	ds_read_b128 v[180:183], v135 offset:19456
	ds_read_b128 v[184:187], v135 offset:20480
	ds_read_b128 v[188:191], v135 offset:21504
	ds_read_b128 v[192:195], v135 offset:22528
	ds_read_b128 v[196:199], v135 offset:23552
	buffer_load_dwordx4 v131, s[36:39], s93 offen lds
	s_mov_b32 m0, s11
	s_add_i32 vcc_lo, s93, 0x160000
	buffer_load_dwordx4 v133, s[36:39], s93 offen lds
	s_mov_b32 m0, s15
	s_nop 0
	buffer_load_dwordx4 v131, s[36:39], vcc_lo offen lds
	s_mov_b32 m0, s16
	s_nop 0
	buffer_load_dwordx4 v133, s[36:39], vcc_lo offen lds
	s_mov_b32 m0, s9
	s_nop 0
	buffer_load_dwordx4 v130, s[40:43], vcc_hi offen lds
	s_mov_b32 m0, s18
	s_nop 0
	buffer_load_dwordx4 v132, s[40:43], vcc_hi offen lds
	s_waitcnt vmcnt(8)
	s_waitcnt lgkmcnt(0)
	s_barrier
	s_setprio 1
	v_mfma_f32_16x16x32_bf16 v[94:97], v[136:139], v[168:171], v[94:97]
	v_mfma_f32_16x16x32_bf16 v[90:93], v[144:147], v[168:171], v[90:93]
	v_mfma_f32_16x16x32_bf16 v[114:117], v[136:139], v[176:179], v[114:117]
	v_mfma_f32_16x16x32_bf16 v[106:109], v[144:147], v[176:179], v[106:109]
	v_mfma_f32_16x16x32_bf16 v[74:77], v[136:139], v[184:187], v[74:77]
	v_mfma_f32_16x16x32_bf16 v[66:69], v[144:147], v[184:187], v[66:69]
	v_mfma_f32_16x16x32_bf16 v[14:17], v[136:139], v[192:195], v[14:17]
	v_mfma_f32_16x16x32_bf16 v[10:13], v[144:147], v[192:195], v[10:13]
	v_mfma_f32_16x16x32_bf16 v[94:97], v[140:143], v[172:175], v[94:97]
	v_mfma_f32_16x16x32_bf16 v[90:93], v[148:151], v[172:175], v[90:93]
	v_mfma_f32_16x16x32_bf16 v[114:117], v[140:143], v[180:183], v[114:117]
	v_mfma_f32_16x16x32_bf16 v[106:109], v[148:151], v[180:183], v[106:109]
	v_mfma_f32_16x16x32_bf16 v[74:77], v[140:143], v[188:191], v[74:77]
	v_mfma_f32_16x16x32_bf16 v[66:69], v[148:151], v[188:191], v[66:69]
	v_mfma_f32_16x16x32_bf16 v[14:17], v[140:143], v[196:199], v[14:17]
	v_mfma_f32_16x16x32_bf16 v[10:13], v[148:151], v[196:199], v[10:13]
	s_setprio 0
	s_setprio 1
	v_mfma_f32_16x16x32_bf16 v[126:129], v[152:155], v[168:171], v[126:129]
	v_mfma_f32_16x16x32_bf16 v[118:121], v[160:163], v[168:171], v[118:121]
	v_mfma_f32_16x16x32_bf16 v[122:125], v[152:155], v[176:179], v[122:125]
	v_mfma_f32_16x16x32_bf16 v[110:113], v[160:163], v[176:179], v[110:113]
	v_mfma_f32_16x16x32_bf16 v[30:33], v[152:155], v[184:187], v[30:33]
	v_mfma_f32_16x16x32_bf16 v[22:25], v[160:163], v[184:187], v[22:25]
	v_mfma_f32_16x16x32_bf16 v[6:9], v[152:155], v[192:195], v[6:9]
	v_mfma_f32_16x16x32_bf16 v[2:5], v[160:163], v[192:195], v[2:5]
	v_mfma_f32_16x16x32_bf16 v[126:129], v[156:159], v[172:175], v[126:129]
	v_mfma_f32_16x16x32_bf16 v[118:121], v[164:167], v[172:175], v[118:121]
	v_mfma_f32_16x16x32_bf16 v[122:125], v[156:159], v[180:183], v[122:125]
	v_mfma_f32_16x16x32_bf16 v[110:113], v[164:167], v[180:183], v[110:113]
	v_mfma_f32_16x16x32_bf16 v[30:33], v[156:159], v[188:191], v[30:33]
	v_mfma_f32_16x16x32_bf16 v[22:25], v[164:167], v[188:191], v[22:25]
	v_mfma_f32_16x16x32_bf16 v[6:9], v[156:159], v[196:199], v[6:9]
	v_mfma_f32_16x16x32_bf16 v[2:5], v[164:167], v[196:199], v[2:5]
	s_setprio 0
	s_barrier
	ds_read_b128 v[136:139], v205
	ds_read_b128 v[140:143], v205 offset:1024
	ds_read_b128 v[144:147], v205 offset:2048
	ds_read_b128 v[148:151], v205 offset:3072
	ds_read_b128 v[152:155], v206
	ds_read_b128 v[156:159], v206 offset:1024
	ds_read_b128 v[160:163], v206 offset:2048
	ds_read_b128 v[164:167], v206 offset:3072
	s_add_i32 vcc_hi, vcc_hi, 0x160000
	s_mov_b32 m0, s19
	ds_read_b128 v[168:171], v135 offset:32768
	ds_read_b128 v[172:175], v135 offset:33792
	ds_read_b128 v[176:179], v135 offset:34816
	ds_read_b128 v[180:183], v135 offset:35840
	ds_read_b128 v[184:187], v135 offset:36864
	ds_read_b128 v[188:191], v135 offset:37888
	ds_read_b128 v[192:195], v135 offset:38912
	ds_read_b128 v[196:199], v135 offset:39936
	buffer_load_dwordx4 v130, s[40:43], vcc_hi offen lds
	s_mov_b32 m0, s20
	s_nop 0
	buffer_load_dwordx4 v132, s[40:43], vcc_hi offen lds
	s_waitcnt vmcnt(8)
	s_waitcnt lgkmcnt(0)
	s_barrier
	s_setprio 1
	v_mfma_f32_16x16x32_bf16 v[26:29], v[136:139], v[168:171], v[26:29]
	v_mfma_f32_16x16x32_bf16 v[18:21], v[144:147], v[168:171], v[18:21]
	v_mfma_f32_16x16x32_bf16 v[42:45], v[136:139], v[176:179], v[42:45]
	v_mfma_f32_16x16x32_bf16 v[34:37], v[144:147], v[176:179], v[34:37]
	v_mfma_f32_16x16x32_bf16 v[54:57], v[136:139], v[184:187], v[54:57]
	v_mfma_f32_16x16x32_bf16 v[50:53], v[144:147], v[184:187], v[50:53]
	v_mfma_f32_16x16x32_bf16 v[78:81], v[136:139], v[192:195], v[78:81]
	v_mfma_f32_16x16x32_bf16 v[70:73], v[144:147], v[192:195], v[70:73]
	v_mfma_f32_16x16x32_bf16 v[26:29], v[140:143], v[172:175], v[26:29]
	v_mfma_f32_16x16x32_bf16 v[18:21], v[148:151], v[172:175], v[18:21]
	v_mfma_f32_16x16x32_bf16 v[42:45], v[140:143], v[180:183], v[42:45]
	v_mfma_f32_16x16x32_bf16 v[34:37], v[148:151], v[180:183], v[34:37]
	v_mfma_f32_16x16x32_bf16 v[54:57], v[140:143], v[188:191], v[54:57]
	v_mfma_f32_16x16x32_bf16 v[50:53], v[148:151], v[188:191], v[50:53]
	v_mfma_f32_16x16x32_bf16 v[78:81], v[140:143], v[196:199], v[78:81]
	v_mfma_f32_16x16x32_bf16 v[70:73], v[148:151], v[196:199], v[70:73]
	s_setprio 0
	s_setprio 1
	v_mfma_f32_16x16x32_bf16 v[46:49], v[152:155], v[168:171], v[46:49]
	v_mfma_f32_16x16x32_bf16 v[38:41], v[160:163], v[168:171], v[38:41]
	v_mfma_f32_16x16x32_bf16 v[62:65], v[152:155], v[176:179], v[62:65]
	v_mfma_f32_16x16x32_bf16 v[58:61], v[160:163], v[176:179], v[58:61]
	v_mfma_f32_16x16x32_bf16 v[86:89], v[152:155], v[184:187], v[86:89]
	v_mfma_f32_16x16x32_bf16 v[82:85], v[160:163], v[184:187], v[82:85]
	v_mfma_f32_16x16x32_bf16 v[102:105], v[152:155], v[192:195], v[102:105]
	v_mfma_f32_16x16x32_bf16 v[98:101], v[160:163], v[192:195], v[98:101]
	v_mfma_f32_16x16x32_bf16 v[46:49], v[156:159], v[172:175], v[46:49]
	v_mfma_f32_16x16x32_bf16 v[38:41], v[164:167], v[172:175], v[38:41]
	v_mfma_f32_16x16x32_bf16 v[62:65], v[156:159], v[180:183], v[62:65]
	v_mfma_f32_16x16x32_bf16 v[58:61], v[164:167], v[180:183], v[58:61]
	v_mfma_f32_16x16x32_bf16 v[86:89], v[156:159], v[188:191], v[86:89]
	v_mfma_f32_16x16x32_bf16 v[82:85], v[164:167], v[188:191], v[82:85]
	v_mfma_f32_16x16x32_bf16 v[102:105], v[156:159], v[196:199], v[102:105]
	v_mfma_f32_16x16x32_bf16 v[98:101], v[164:167], v[196:199], v[98:101]
	s_setprio 0
	s_barrier
	s_mov_b32 m0, s21
	s_or_b32 vcc_lo, s93, 0x80
	ds_read_b128 v[168:171], v135 offset:49152
	ds_read_b128 v[172:175], v135 offset:50176
	ds_read_b128 v[176:179], v135 offset:51200
	ds_read_b128 v[180:183], v135 offset:52224
	ds_read_b128 v[184:187], v135 offset:53248
	ds_read_b128 v[188:191], v135 offset:54272
	ds_read_b128 v[192:195], v135 offset:55296
	ds_read_b128 v[196:199], v135 offset:56320
	buffer_load_dwordx4 v131, s[36:39], vcc_lo offen lds
	s_mov_b32 m0, s64
	s_add_i32 s93, s93, 0x160080
	buffer_load_dwordx4 v133, s[36:39], vcc_lo offen lds
	s_mov_b32 m0, s78
	s_nop 0
	buffer_load_dwordx4 v131, s[36:39], s93 offen lds
	s_mov_b32 m0, s79
	s_nop 0
	buffer_load_dwordx4 v133, s[36:39], s93 offen lds
	s_mov_b32 m0, s65
	s_nop 0
	buffer_load_dwordx4 v130, s[40:43], s91 offen lds
	s_mov_b32 m0, s67
	s_nop 0
	buffer_load_dwordx4 v132, s[40:43], s91 offen lds
	s_waitcnt vmcnt(8)
	s_waitcnt lgkmcnt(0)
	s_barrier
	s_setprio 1
	v_mfma_f32_16x16x32_bf16 v[94:97], v[136:139], v[168:171], v[94:97]
	v_mfma_f32_16x16x32_bf16 v[90:93], v[144:147], v[168:171], v[90:93]
	v_mfma_f32_16x16x32_bf16 v[114:117], v[136:139], v[176:179], v[114:117]
	v_mfma_f32_16x16x32_bf16 v[106:109], v[144:147], v[176:179], v[106:109]
	v_mfma_f32_16x16x32_bf16 v[74:77], v[136:139], v[184:187], v[74:77]
	v_mfma_f32_16x16x32_bf16 v[66:69], v[144:147], v[184:187], v[66:69]
	v_mfma_f32_16x16x32_bf16 v[14:17], v[136:139], v[192:195], v[14:17]
	v_mfma_f32_16x16x32_bf16 v[10:13], v[144:147], v[192:195], v[10:13]
	v_mfma_f32_16x16x32_bf16 v[94:97], v[140:143], v[172:175], v[94:97]
	v_mfma_f32_16x16x32_bf16 v[90:93], v[148:151], v[172:175], v[90:93]
	v_mfma_f32_16x16x32_bf16 v[114:117], v[140:143], v[180:183], v[114:117]
	v_mfma_f32_16x16x32_bf16 v[106:109], v[148:151], v[180:183], v[106:109]
	v_mfma_f32_16x16x32_bf16 v[74:77], v[140:143], v[188:191], v[74:77]
	v_mfma_f32_16x16x32_bf16 v[66:69], v[148:151], v[188:191], v[66:69]
	v_mfma_f32_16x16x32_bf16 v[14:17], v[140:143], v[196:199], v[14:17]
	v_mfma_f32_16x16x32_bf16 v[10:13], v[148:151], v[196:199], v[10:13]
	s_setprio 0
	s_setprio 1
	v_mfma_f32_16x16x32_bf16 v[126:129], v[152:155], v[168:171], v[126:129]
	v_mfma_f32_16x16x32_bf16 v[118:121], v[160:163], v[168:171], v[118:121]
	v_mfma_f32_16x16x32_bf16 v[122:125], v[152:155], v[176:179], v[122:125]
	v_mfma_f32_16x16x32_bf16 v[110:113], v[160:163], v[176:179], v[110:113]
	v_mfma_f32_16x16x32_bf16 v[30:33], v[152:155], v[184:187], v[30:33]
	v_mfma_f32_16x16x32_bf16 v[22:25], v[160:163], v[184:187], v[22:25]
	v_mfma_f32_16x16x32_bf16 v[6:9], v[152:155], v[192:195], v[6:9]
	v_mfma_f32_16x16x32_bf16 v[2:5], v[160:163], v[192:195], v[2:5]
	v_mfma_f32_16x16x32_bf16 v[126:129], v[156:159], v[172:175], v[126:129]
	v_mfma_f32_16x16x32_bf16 v[118:121], v[164:167], v[172:175], v[118:121]
	v_mfma_f32_16x16x32_bf16 v[122:125], v[156:159], v[180:183], v[122:125]
	v_mfma_f32_16x16x32_bf16 v[110:113], v[164:167], v[180:183], v[110:113]
	v_mfma_f32_16x16x32_bf16 v[30:33], v[156:159], v[188:191], v[30:33]
	v_mfma_f32_16x16x32_bf16 v[22:25], v[164:167], v[188:191], v[22:25]
	v_mfma_f32_16x16x32_bf16 v[6:9], v[156:159], v[196:199], v[6:9]
	v_mfma_f32_16x16x32_bf16 v[2:5], v[164:167], v[196:199], v[2:5]
	s_setprio 0
	s_barrier
	s_add_i32 s89, s89, 2
	s_addk_i32 s90, 0x100
	s_cmpk_lt_u32 s89, 0x56
	s_cbranch_scc1 .LBB0_366
	s_waitcnt vmcnt(0)
	s_cmpk_gt_u32 s66, 0xff
	s_cbranch_scc1 .LBB0_369
	s_barrier

.LBB0_816:
	ds_read_b128 v[134:137], v218
	ds_read_b128 v[158:161], v218 offset:1024
	ds_read_b128 v[162:165], v218 offset:2048
	ds_read_b128 v[166:169], v218 offset:3072
	ds_read_b128 v[170:173], v219
	ds_read_b128 v[174:177], v219 offset:1024
	ds_read_b128 v[178:181], v219 offset:2048
	ds_read_b128 v[182:185], v219 offset:3072
	s_add_i32 s47, s66, 0xfff80080
	s_cmp_eq_u32 s76, 28
	s_cselect_b32 s79, s64, s47
	s_cselect_b32 s78, s65, s67
	s_or_b32 s77, s79, 0x80
	s_mov_b32 s47, s31
	s_mov_b32 m0, s53
	ds_read_b128 v[186:189], v156
	ds_read_b128 v[190:193], v156 offset:1024
	ds_read_b128 v[194:197], v156 offset:2048
	ds_read_b128 v[198:201], v156 offset:3072
	ds_read_b128 v[202:205], v156 offset:4096
	ds_read_b128 v[206:209], v156 offset:5120
	ds_read_b128 v[210:213], v156 offset:6144
	ds_read_b128 v[214:217], v156 offset:7168
	buffer_load_dwordx4 v131, s[44:47], s66 offen lds
	s_mov_b32 m0, s56
	s_nop 0
	buffer_load_dwordx4 v150, s[44:47], s66 offen lds
	s_waitcnt vmcnt(8)
	s_waitcnt lgkmcnt(0)
	s_barrier
	s_setprio 1
	v_mfma_f32_16x16x32_bf16 v[126:129], v[134:137], v[186:189], v[126:129]
	v_mfma_f32_16x16x32_bf16 v[122:125], v[162:165], v[186:189], v[122:125]
	v_mfma_f32_16x16x32_bf16 v[118:121], v[134:137], v[194:197], v[118:121]
	v_mfma_f32_16x16x32_bf16 v[110:113], v[162:165], v[194:197], v[110:113]
	v_mfma_f32_16x16x32_bf16 v[102:105], v[134:137], v[202:205], v[102:105]
	v_mfma_f32_16x16x32_bf16 v[94:97], v[162:165], v[202:205], v[94:97]
	v_mfma_f32_16x16x32_bf16 v[86:89], v[134:137], v[210:213], v[86:89]
	v_mfma_f32_16x16x32_bf16 v[78:81], v[162:165], v[210:213], v[78:81]
	v_mfma_f32_16x16x32_bf16 v[126:129], v[158:161], v[190:193], v[126:129]
	v_mfma_f32_16x16x32_bf16 v[122:125], v[166:169], v[190:193], v[122:125]
	v_mfma_f32_16x16x32_bf16 v[118:121], v[158:161], v[198:201], v[118:121]
	v_mfma_f32_16x16x32_bf16 v[110:113], v[166:169], v[198:201], v[110:113]
	v_mfma_f32_16x16x32_bf16 v[102:105], v[158:161], v[206:209], v[102:105]
	v_mfma_f32_16x16x32_bf16 v[94:97], v[166:169], v[206:209], v[94:97]
	v_mfma_f32_16x16x32_bf16 v[86:89], v[158:161], v[214:217], v[86:89]
	v_mfma_f32_16x16x32_bf16 v[78:81], v[166:169], v[214:217], v[78:81]
	s_setprio 0
	s_setprio 1
	v_mfma_f32_16x16x32_bf16 v[114:117], v[170:173], v[186:189], v[114:117]
	v_mfma_f32_16x16x32_bf16 v[106:109], v[178:181], v[186:189], v[106:109]
	v_mfma_f32_16x16x32_bf16 v[98:101], v[170:173], v[194:197], v[98:101]
	v_mfma_f32_16x16x32_bf16 v[90:93], v[178:181], v[194:197], v[90:93]
	v_mfma_f32_16x16x32_bf16 v[82:85], v[170:173], v[202:205], v[82:85]
	v_mfma_f32_16x16x32_bf16 v[74:77], v[178:181], v[202:205], v[74:77]
	v_mfma_f32_16x16x32_bf16 v[70:73], v[170:173], v[210:213], v[70:73]
	v_mfma_f32_16x16x32_bf16 v[66:69], v[178:181], v[210:213], v[66:69]
	v_mfma_f32_16x16x32_bf16 v[114:117], v[174:177], v[190:193], v[114:117]
	v_mfma_f32_16x16x32_bf16 v[106:109], v[182:185], v[190:193], v[106:109]
	v_mfma_f32_16x16x32_bf16 v[98:101], v[174:177], v[198:201], v[98:101]
	v_mfma_f32_16x16x32_bf16 v[90:93], v[182:185], v[198:201], v[90:93]
	v_mfma_f32_16x16x32_bf16 v[82:85], v[174:177], v[206:209], v[82:85]
	v_mfma_f32_16x16x32_bf16 v[74:77], v[182:185], v[206:209], v[74:77]
	v_mfma_f32_16x16x32_bf16 v[70:73], v[174:177], v[214:217], v[70:73]
	v_mfma_f32_16x16x32_bf16 v[66:69], v[182:185], v[214:217], v[66:69]
	s_setprio 0
	s_barrier
	s_mov_b32 m0, s18
	s_mov_b32 s51, s31
	ds_read_b128 v[186:189], v156 offset:16384
	ds_read_b128 v[190:193], v156 offset:17408
	ds_read_b128 v[194:197], v156 offset:18432
	ds_read_b128 v[198:201], v156 offset:19456
	ds_read_b128 v[202:205], v156 offset:20480
	ds_read_b128 v[206:209], v156 offset:21504
	ds_read_b128 v[210:213], v156 offset:22528
	ds_read_b128 v[214:217], v156 offset:23552
	buffer_load_dwordx4 v149, s[48:51], s78 offen lds
	s_mov_b32 m0, s19
	s_add_i32 s80, s78, 0x80000
	buffer_load_dwordx4 v151, s[48:51], s78 offen lds
	s_mov_b32 m0, s22
	s_nop 0
	buffer_load_dwordx4 v149, s[48:51], s80 offen lds
	s_mov_b32 m0, s23
	s_nop 0
	buffer_load_dwordx4 v151, s[48:51], s80 offen lds
	s_mov_b32 m0, s17
	s_nop 0
	buffer_load_dwordx4 v131, s[44:47], s79 offen lds
	s_mov_b32 m0, s28
	s_nop 0
	buffer_load_dwordx4 v150, s[44:47], s79 offen lds
	s_waitcnt vmcnt(8)
	s_waitcnt lgkmcnt(0)
	s_barrier
	s_setprio 1
	v_mfma_f32_16x16x32_bf16 v[62:65], v[134:137], v[186:189], v[62:65]
	v_mfma_f32_16x16x32_bf16 v[58:61], v[162:165], v[186:189], v[58:61]
	v_mfma_f32_16x16x32_bf16 v[54:57], v[134:137], v[194:197], v[54:57]
	v_mfma_f32_16x16x32_bf16 v[46:49], v[162:165], v[194:197], v[46:49]
	v_mfma_f32_16x16x32_bf16 v[38:41], v[134:137], v[202:205], v[38:41]
	v_mfma_f32_16x16x32_bf16 v[30:33], v[162:165], v[202:205], v[30:33]
	v_mfma_f32_16x16x32_bf16 v[22:25], v[134:137], v[210:213], v[22:25]
	v_mfma_f32_16x16x32_bf16 v[14:17], v[162:165], v[210:213], v[14:17]
	v_mfma_f32_16x16x32_bf16 v[62:65], v[158:161], v[190:193], v[62:65]
	v_mfma_f32_16x16x32_bf16 v[58:61], v[166:169], v[190:193], v[58:61]
	v_mfma_f32_16x16x32_bf16 v[54:57], v[158:161], v[198:201], v[54:57]
	v_mfma_f32_16x16x32_bf16 v[46:49], v[166:169], v[198:201], v[46:49]
	v_mfma_f32_16x16x32_bf16 v[38:41], v[158:161], v[206:209], v[38:41]
	v_mfma_f32_16x16x32_bf16 v[30:33], v[166:169], v[206:209], v[30:33]
	v_mfma_f32_16x16x32_bf16 v[22:25], v[158:161], v[214:217], v[22:25]
	v_mfma_f32_16x16x32_bf16 v[14:17], v[166:169], v[214:217], v[14:17]
	s_setprio 0
	s_setprio 1
	v_mfma_f32_16x16x32_bf16 v[50:53], v[170:173], v[186:189], v[50:53]
	v_mfma_f32_16x16x32_bf16 v[42:45], v[178:181], v[186:189], v[42:45]
	v_mfma_f32_16x16x32_bf16 v[34:37], v[170:173], v[194:197], v[34:37]
	v_mfma_f32_16x16x32_bf16 v[26:29], v[178:181], v[194:197], v[26:29]
	v_mfma_f32_16x16x32_bf16 v[18:21], v[170:173], v[202:205], v[18:21]
	v_mfma_f32_16x16x32_bf16 v[10:13], v[178:181], v[202:205], v[10:13]
	v_mfma_f32_16x16x32_bf16 v[6:9], v[170:173], v[210:213], v[6:9]
	v_mfma_f32_16x16x32_bf16 v[2:5], v[178:181], v[210:213], v[2:5]
	v_mfma_f32_16x16x32_bf16 v[50:53], v[174:177], v[190:193], v[50:53]
	v_mfma_f32_16x16x32_bf16 v[42:45], v[182:185], v[190:193], v[42:45]
	v_mfma_f32_16x16x32_bf16 v[34:37], v[174:177], v[198:201], v[34:37]
	v_mfma_f32_16x16x32_bf16 v[26:29], v[182:185], v[198:201], v[26:29]
	v_mfma_f32_16x16x32_bf16 v[18:21], v[174:177], v[206:209], v[18:21]
	v_mfma_f32_16x16x32_bf16 v[10:13], v[182:185], v[206:209], v[10:13]
	v_mfma_f32_16x16x32_bf16 v[6:9], v[174:177], v[214:217], v[6:9]
	v_mfma_f32_16x16x32_bf16 v[2:5], v[182:185], v[214:217], v[2:5]
	s_setprio 0
	s_barrier
	ds_read_b128 v[134:137], v220
	ds_read_b128 v[158:161], v220 offset:1024
	ds_read_b128 v[162:165], v220 offset:2048
	ds_read_b128 v[166:169], v220 offset:3072
	ds_read_b128 v[170:173], v221
	ds_read_b128 v[174:177], v221 offset:1024
	ds_read_b128 v[178:181], v221 offset:2048
	ds_read_b128 v[182:185], v221 offset:3072
	s_add_i32 s79, s79, 0x80000
	s_mov_b32 m0, s29
	ds_read_b128 v[186:189], v156 offset:32768
	ds_read_b128 v[190:193], v156 offset:33792
	ds_read_b128 v[194:197], v156 offset:34816
	ds_read_b128 v[198:201], v156 offset:35840
	ds_read_b128 v[202:205], v156 offset:36864
	ds_read_b128 v[206:209], v156 offset:37888
	ds_read_b128 v[210:213], v156 offset:38912
	ds_read_b128 v[214:217], v156 offset:39936
	buffer_load_dwordx4 v131, s[44:47], s79 offen lds
	s_mov_b32 m0, s34
	s_nop 0
	buffer_load_dwordx4 v150, s[44:47], s79 offen lds
	s_waitcnt vmcnt(8)
	s_waitcnt lgkmcnt(0)
	s_barrier
	s_setprio 1
	v_mfma_f32_16x16x32_bf16 v[126:129], v[134:137], v[186:189], v[126:129]
	v_mfma_f32_16x16x32_bf16 v[122:125], v[162:165], v[186:189], v[122:125]
	v_mfma_f32_16x16x32_bf16 v[118:121], v[134:137], v[194:197], v[118:121]
	v_mfma_f32_16x16x32_bf16 v[110:113], v[162:165], v[194:197], v[110:113]
	v_mfma_f32_16x16x32_bf16 v[102:105], v[134:137], v[202:205], v[102:105]
	v_mfma_f32_16x16x32_bf16 v[94:97], v[162:165], v[202:205], v[94:97]
	v_mfma_f32_16x16x32_bf16 v[86:89], v[134:137], v[210:213], v[86:89]
	v_mfma_f32_16x16x32_bf16 v[78:81], v[162:165], v[210:213], v[78:81]
	v_mfma_f32_16x16x32_bf16 v[126:129], v[158:161], v[190:193], v[126:129]
	v_mfma_f32_16x16x32_bf16 v[122:125], v[166:169], v[190:193], v[122:125]
	v_mfma_f32_16x16x32_bf16 v[118:121], v[158:161], v[198:201], v[118:121]
	v_mfma_f32_16x16x32_bf16 v[110:113], v[166:169], v[198:201], v[110:113]
	v_mfma_f32_16x16x32_bf16 v[102:105], v[158:161], v[206:209], v[102:105]
	v_mfma_f32_16x16x32_bf16 v[94:97], v[166:169], v[206:209], v[94:97]
	v_mfma_f32_16x16x32_bf16 v[86:89], v[158:161], v[214:217], v[86:89]
	v_mfma_f32_16x16x32_bf16 v[78:81], v[166:169], v[214:217], v[78:81]
	s_setprio 0
	s_setprio 1
	v_mfma_f32_16x16x32_bf16 v[114:117], v[170:173], v[186:189], v[114:117]
	v_mfma_f32_16x16x32_bf16 v[106:109], v[178:181], v[186:189], v[106:109]
	v_mfma_f32_16x16x32_bf16 v[98:101], v[170:173], v[194:197], v[98:101]
	v_mfma_f32_16x16x32_bf16 v[90:93], v[178:181], v[194:197], v[90:93]
	v_mfma_f32_16x16x32_bf16 v[82:85], v[170:173], v[202:205], v[82:85]
	v_mfma_f32_16x16x32_bf16 v[74:77], v[178:181], v[202:205], v[74:77]
	v_mfma_f32_16x16x32_bf16 v[70:73], v[170:173], v[210:213], v[70:73]
	v_mfma_f32_16x16x32_bf16 v[66:69], v[178:181], v[210:213], v[66:69]
	v_mfma_f32_16x16x32_bf16 v[114:117], v[174:177], v[190:193], v[114:117]
	v_mfma_f32_16x16x32_bf16 v[106:109], v[182:185], v[190:193], v[106:109]
	v_mfma_f32_16x16x32_bf16 v[98:101], v[174:177], v[198:201], v[98:101]
	v_mfma_f32_16x16x32_bf16 v[90:93], v[182:185], v[198:201], v[90:93]
	v_mfma_f32_16x16x32_bf16 v[82:85], v[174:177], v[206:209], v[82:85]
	v_mfma_f32_16x16x32_bf16 v[74:77], v[182:185], v[206:209], v[74:77]
	v_mfma_f32_16x16x32_bf16 v[70:73], v[174:177], v[214:217], v[70:73]
	v_mfma_f32_16x16x32_bf16 v[66:69], v[182:185], v[214:217], v[66:69]
	s_setprio 0
	s_barrier
	s_mov_b32 m0, s35
	s_or_b32 s79, s78, 0x80
	ds_read_b128 v[186:189], v156 offset:49152
	ds_read_b128 v[190:193], v156 offset:50176
	ds_read_b128 v[194:197], v156 offset:51200
	ds_read_b128 v[198:201], v156 offset:52224
	ds_read_b128 v[202:205], v156 offset:53248
	ds_read_b128 v[206:209], v156 offset:54272
	ds_read_b128 v[210:213], v156 offset:55296
	ds_read_b128 v[214:217], v156 offset:56320
	buffer_load_dwordx4 v149, s[48:51], s79 offen lds
	s_mov_b32 m0, s36
	s_add_i32 s78, s78, 0x80080
	buffer_load_dwordx4 v151, s[48:51], s79 offen lds
	s_mov_b32 m0, s41
	s_nop 0
	buffer_load_dwordx4 v149, s[48:51], s78 offen lds
	s_mov_b32 m0, s52
	s_nop 0
	buffer_load_dwordx4 v151, s[48:51], s78 offen lds
	s_mov_b32 m0, s37
	s_nop 0
	buffer_load_dwordx4 v131, s[44:47], s77 offen lds
	s_mov_b32 m0, s40
	s_nop 0
	buffer_load_dwordx4 v150, s[44:47], s77 offen lds
	s_waitcnt vmcnt(8)
	s_waitcnt lgkmcnt(0)
	s_barrier
	s_setprio 1
	v_mfma_f32_16x16x32_bf16 v[62:65], v[134:137], v[186:189], v[62:65]
	v_mfma_f32_16x16x32_bf16 v[58:61], v[162:165], v[186:189], v[58:61]
	v_mfma_f32_16x16x32_bf16 v[54:57], v[134:137], v[194:197], v[54:57]
	v_mfma_f32_16x16x32_bf16 v[46:49], v[162:165], v[194:197], v[46:49]
	v_mfma_f32_16x16x32_bf16 v[38:41], v[134:137], v[202:205], v[38:41]
	v_mfma_f32_16x16x32_bf16 v[30:33], v[162:165], v[202:205], v[30:33]
	v_mfma_f32_16x16x32_bf16 v[22:25], v[134:137], v[210:213], v[22:25]
	v_mfma_f32_16x16x32_bf16 v[14:17], v[162:165], v[210:213], v[14:17]
	v_mfma_f32_16x16x32_bf16 v[62:65], v[158:161], v[190:193], v[62:65]
	v_mfma_f32_16x16x32_bf16 v[58:61], v[166:169], v[190:193], v[58:61]
	v_mfma_f32_16x16x32_bf16 v[54:57], v[158:161], v[198:201], v[54:57]
	v_mfma_f32_16x16x32_bf16 v[46:49], v[166:169], v[198:201], v[46:49]
	v_mfma_f32_16x16x32_bf16 v[38:41], v[158:161], v[206:209], v[38:41]
	v_mfma_f32_16x16x32_bf16 v[30:33], v[166:169], v[206:209], v[30:33]
	v_mfma_f32_16x16x32_bf16 v[22:25], v[158:161], v[214:217], v[22:25]
	v_mfma_f32_16x16x32_bf16 v[14:17], v[166:169], v[214:217], v[14:17]
	s_setprio 0
	s_setprio 1
	v_mfma_f32_16x16x32_bf16 v[50:53], v[170:173], v[186:189], v[50:53]
	v_mfma_f32_16x16x32_bf16 v[42:45], v[178:181], v[186:189], v[42:45]
	v_mfma_f32_16x16x32_bf16 v[34:37], v[170:173], v[194:197], v[34:37]
	v_mfma_f32_16x16x32_bf16 v[26:29], v[178:181], v[194:197], v[26:29]
	v_mfma_f32_16x16x32_bf16 v[18:21], v[170:173], v[202:205], v[18:21]
	v_mfma_f32_16x16x32_bf16 v[10:13], v[178:181], v[202:205], v[10:13]
	v_mfma_f32_16x16x32_bf16 v[6:9], v[170:173], v[210:213], v[6:9]
	v_mfma_f32_16x16x32_bf16 v[2:5], v[178:181], v[210:213], v[2:5]
	v_mfma_f32_16x16x32_bf16 v[50:53], v[174:177], v[190:193], v[50:53]
	v_mfma_f32_16x16x32_bf16 v[42:45], v[182:185], v[190:193], v[42:45]
	v_mfma_f32_16x16x32_bf16 v[34:37], v[174:177], v[198:201], v[34:37]
	v_mfma_f32_16x16x32_bf16 v[26:29], v[182:185], v[198:201], v[26:29]
	v_mfma_f32_16x16x32_bf16 v[18:21], v[174:177], v[206:209], v[18:21]
	v_mfma_f32_16x16x32_bf16 v[10:13], v[182:185], v[206:209], v[10:13]
	v_mfma_f32_16x16x32_bf16 v[6:9], v[174:177], v[214:217], v[6:9]
	v_mfma_f32_16x16x32_bf16 v[2:5], v[182:185], v[214:217], v[2:5]
	s_setprio 0
	s_barrier
	s_add_i32 s76, s76, 2
	s_addk_i32 s66, 0x100
	s_addk_i32 s67, 0x100
	s_cmp_gt_u32 s76, 29
	s_cbranch_scc0 .LBB0_816
	s_and_b64 vcc, exec, s[10:11]
	s_cbranch_vccz .LBB0_819
	s_barrier

.LBB0_844:
	ds_read_b128 v[122:125], v218
	ds_read_b128 v[126:129], v218 offset:1024
	ds_read_b128 v[130:133], v218 offset:2048
	ds_read_b128 v[134:137], v218 offset:3072
	ds_read_b128 v[162:165], v219
	ds_read_b128 v[166:169], v219 offset:1024
	ds_read_b128 v[170:173], v219 offset:2048
	ds_read_b128 v[174:177], v219 offset:3072
	s_add_i32 s55, s76, 0xfffc0080
	s_cmp_eq_u32 s78, 12
	s_cselect_b32 s82, s66, s55
	s_cselect_b32 s80, s67, s77
	s_or_b32 s79, s82, 0x80
	s_mov_b32 m0, s59
	ds_read_b128 v[178:181], v160
	ds_read_b128 v[182:185], v160 offset:1024
	ds_read_b128 v[186:189], v160 offset:2048
	ds_read_b128 v[190:193], v160 offset:3072
	ds_read_b128 v[194:197], v160 offset:4096
	ds_read_b128 v[198:201], v160 offset:5120
	ds_read_b128 v[202:205], v160 offset:6144
	ds_read_b128 v[206:209], v160 offset:7168
	buffer_load_dwordx4 v153, s[28:31], s76 offen lds
	s_mov_b32 m0, s60
	s_nop 0
	buffer_load_dwordx4 v155, s[28:31], s76 offen lds
	s_waitcnt vmcnt(8)
	s_waitcnt lgkmcnt(0)
	s_barrier
	s_setprio 1
	v_mfma_i32_16x16x64_i8 v[142:145], v[122:125], v[178:181], v[142:145]
	v_mfma_i32_16x16x64_i8 v[138:141], v[130:133], v[178:181], v[138:141]
	v_mfma_i32_16x16x64_i8 v[110:113], v[122:125], v[186:189], v[110:113]
	v_mfma_i32_16x16x64_i8 v[106:109], v[130:133], v[186:189], v[106:109]
	v_mfma_i32_16x16x64_i8 v[94:97], v[122:125], v[194:197], v[94:97]
	v_mfma_i32_16x16x64_i8 v[90:93], v[130:133], v[194:197], v[90:93]
	v_mfma_i32_16x16x64_i8 v[78:81], v[122:125], v[202:205], v[78:81]
	v_mfma_i32_16x16x64_i8 v[74:77], v[130:133], v[202:205], v[74:77]
	v_mfma_i32_16x16x64_i8 v[142:145], v[126:129], v[182:185], v[142:145]
	v_mfma_i32_16x16x64_i8 v[138:141], v[134:137], v[182:185], v[138:141]
	v_mfma_i32_16x16x64_i8 v[110:113], v[126:129], v[190:193], v[110:113]
	v_mfma_i32_16x16x64_i8 v[106:109], v[134:137], v[190:193], v[106:109]
	v_mfma_i32_16x16x64_i8 v[94:97], v[126:129], v[198:201], v[94:97]
	v_mfma_i32_16x16x64_i8 v[90:93], v[134:137], v[198:201], v[90:93]
	v_mfma_i32_16x16x64_i8 v[78:81], v[126:129], v[206:209], v[78:81]
	v_mfma_i32_16x16x64_i8 v[74:77], v[134:137], v[206:209], v[74:77]
	s_setprio 0
	s_setprio 1
	v_mfma_i32_16x16x64_i8 v[118:121], v[162:165], v[178:181], v[118:121]
	v_mfma_i32_16x16x64_i8 v[114:117], v[170:173], v[178:181], v[114:117]
	v_mfma_i32_16x16x64_i8 v[102:105], v[162:165], v[186:189], v[102:105]
	v_mfma_i32_16x16x64_i8 v[98:101], v[170:173], v[186:189], v[98:101]
	v_mfma_i32_16x16x64_i8 v[86:89], v[162:165], v[194:197], v[86:89]
	v_mfma_i32_16x16x64_i8 v[82:85], v[170:173], v[194:197], v[82:85]
	v_mfma_i32_16x16x64_i8 v[70:73], v[162:165], v[202:205], v[70:73]
	v_mfma_i32_16x16x64_i8 v[66:69], v[170:173], v[202:205], v[66:69]
	v_mfma_i32_16x16x64_i8 v[118:121], v[166:169], v[182:185], v[118:121]
	v_mfma_i32_16x16x64_i8 v[114:117], v[174:177], v[182:185], v[114:117]
	v_mfma_i32_16x16x64_i8 v[102:105], v[166:169], v[190:193], v[102:105]
	v_mfma_i32_16x16x64_i8 v[98:101], v[174:177], v[190:193], v[98:101]
	v_mfma_i32_16x16x64_i8 v[86:89], v[166:169], v[198:201], v[86:89]
	v_mfma_i32_16x16x64_i8 v[82:85], v[174:177], v[198:201], v[82:85]
	v_mfma_i32_16x16x64_i8 v[70:73], v[166:169], v[206:209], v[70:73]
	v_mfma_i32_16x16x64_i8 v[66:69], v[174:177], v[206:209], v[66:69]
	s_setprio 0
	s_barrier
	s_mov_b32 m0, s34
	s_mov_b32 s55, s31
	ds_read_b128 v[178:181], v160 offset:16384
	ds_read_b128 v[182:185], v160 offset:17408
	ds_read_b128 v[186:189], v160 offset:18432
	ds_read_b128 v[190:193], v160 offset:19456
	ds_read_b128 v[194:197], v160 offset:20480
	ds_read_b128 v[198:201], v160 offset:21504
	ds_read_b128 v[202:205], v160 offset:22528
	ds_read_b128 v[206:209], v160 offset:23552
	buffer_load_dwordx4 v154, s[52:55], s80 offen lds
	s_mov_b32 m0, s35
	s_add_i32 s83, s80, 0x40000
	buffer_load_dwordx4 v156, s[52:55], s80 offen lds
	s_mov_b32 m0, s36
	s_nop 0
	buffer_load_dwordx4 v154, s[52:55], s83 offen lds
	s_mov_b32 m0, s37
	s_nop 0
	buffer_load_dwordx4 v156, s[52:55], s83 offen lds
	s_mov_b32 m0, s23
	s_nop 0
	buffer_load_dwordx4 v153, s[28:31], s82 offen lds
	s_mov_b32 m0, s40
	s_nop 0
	buffer_load_dwordx4 v155, s[28:31], s82 offen lds
	s_waitcnt vmcnt(8)
	s_waitcnt lgkmcnt(0)
	s_barrier
	s_setprio 1
	v_mfma_i32_16x16x64_i8 v[62:65], v[122:125], v[178:181], v[62:65]
	v_mfma_i32_16x16x64_i8 v[58:61], v[130:133], v[178:181], v[58:61]
	v_mfma_i32_16x16x64_i8 v[46:49], v[122:125], v[186:189], v[46:49]
	v_mfma_i32_16x16x64_i8 v[42:45], v[130:133], v[186:189], v[42:45]
	v_mfma_i32_16x16x64_i8 v[30:33], v[122:125], v[194:197], v[30:33]
	v_mfma_i32_16x16x64_i8 v[26:29], v[130:133], v[194:197], v[26:29]
	v_mfma_i32_16x16x64_i8 v[14:17], v[122:125], v[202:205], v[14:17]
	v_mfma_i32_16x16x64_i8 v[10:13], v[130:133], v[202:205], v[10:13]
	v_mfma_i32_16x16x64_i8 v[62:65], v[126:129], v[182:185], v[62:65]
	v_mfma_i32_16x16x64_i8 v[58:61], v[134:137], v[182:185], v[58:61]
	v_mfma_i32_16x16x64_i8 v[46:49], v[126:129], v[190:193], v[46:49]
	v_mfma_i32_16x16x64_i8 v[42:45], v[134:137], v[190:193], v[42:45]
	v_mfma_i32_16x16x64_i8 v[30:33], v[126:129], v[198:201], v[30:33]
	v_mfma_i32_16x16x64_i8 v[26:29], v[134:137], v[198:201], v[26:29]
	v_mfma_i32_16x16x64_i8 v[14:17], v[126:129], v[206:209], v[14:17]
	v_mfma_i32_16x16x64_i8 v[10:13], v[134:137], v[206:209], v[10:13]
	s_setprio 0
	s_setprio 1
	v_mfma_i32_16x16x64_i8 v[54:57], v[162:165], v[178:181], v[54:57]
	v_mfma_i32_16x16x64_i8 v[50:53], v[170:173], v[178:181], v[50:53]
	v_mfma_i32_16x16x64_i8 v[38:41], v[162:165], v[186:189], v[38:41]
	v_mfma_i32_16x16x64_i8 v[34:37], v[170:173], v[186:189], v[34:37]
	v_mfma_i32_16x16x64_i8 v[22:25], v[162:165], v[194:197], v[22:25]
	v_mfma_i32_16x16x64_i8 v[18:21], v[170:173], v[194:197], v[18:21]
	v_mfma_i32_16x16x64_i8 v[6:9], v[162:165], v[202:205], v[6:9]
	v_mfma_i32_16x16x64_i8 v[2:5], v[170:173], v[202:205], v[2:5]
	v_mfma_i32_16x16x64_i8 v[54:57], v[166:169], v[182:185], v[54:57]
	v_mfma_i32_16x16x64_i8 v[50:53], v[174:177], v[182:185], v[50:53]
	v_mfma_i32_16x16x64_i8 v[38:41], v[166:169], v[190:193], v[38:41]
	v_mfma_i32_16x16x64_i8 v[34:37], v[174:177], v[190:193], v[34:37]
	v_mfma_i32_16x16x64_i8 v[22:25], v[166:169], v[198:201], v[22:25]
	v_mfma_i32_16x16x64_i8 v[18:21], v[174:177], v[198:201], v[18:21]
	v_mfma_i32_16x16x64_i8 v[6:9], v[166:169], v[206:209], v[6:9]
	v_mfma_i32_16x16x64_i8 v[2:5], v[174:177], v[206:209], v[2:5]
	s_setprio 0
	s_barrier
	ds_read_b128 v[122:125], v220
	ds_read_b128 v[126:129], v220 offset:1024
	ds_read_b128 v[130:133], v220 offset:2048
	ds_read_b128 v[134:137], v220 offset:3072
	ds_read_b128 v[162:165], v221
	ds_read_b128 v[166:169], v221 offset:1024
	ds_read_b128 v[170:173], v221 offset:2048
	ds_read_b128 v[174:177], v221 offset:3072
	s_add_i32 s82, s82, 0x40000
	s_mov_b32 m0, s41
	ds_read_b128 v[178:181], v160 offset:32768
	ds_read_b128 v[182:185], v160 offset:33792
	ds_read_b128 v[186:189], v160 offset:34816
	ds_read_b128 v[190:193], v160 offset:35840
	ds_read_b128 v[194:197], v160 offset:36864
	ds_read_b128 v[198:201], v160 offset:37888
	ds_read_b128 v[202:205], v160 offset:38912
	ds_read_b128 v[206:209], v160 offset:39936
	buffer_load_dwordx4 v153, s[28:31], s82 offen lds
	s_mov_b32 m0, s43
	s_nop 0
	buffer_load_dwordx4 v155, s[28:31], s82 offen lds
	s_waitcnt vmcnt(8)
	s_waitcnt lgkmcnt(0)
	s_barrier
	s_setprio 1
	v_mfma_i32_16x16x64_i8 v[142:145], v[122:125], v[178:181], v[142:145]
	v_mfma_i32_16x16x64_i8 v[138:141], v[130:133], v[178:181], v[138:141]
	v_mfma_i32_16x16x64_i8 v[110:113], v[122:125], v[186:189], v[110:113]
	v_mfma_i32_16x16x64_i8 v[106:109], v[130:133], v[186:189], v[106:109]
	v_mfma_i32_16x16x64_i8 v[94:97], v[122:125], v[194:197], v[94:97]
	v_mfma_i32_16x16x64_i8 v[90:93], v[130:133], v[194:197], v[90:93]
	v_mfma_i32_16x16x64_i8 v[78:81], v[122:125], v[202:205], v[78:81]
	v_mfma_i32_16x16x64_i8 v[74:77], v[130:133], v[202:205], v[74:77]
	v_mfma_i32_16x16x64_i8 v[142:145], v[126:129], v[182:185], v[142:145]
	v_mfma_i32_16x16x64_i8 v[138:141], v[134:137], v[182:185], v[138:141]
	v_mfma_i32_16x16x64_i8 v[110:113], v[126:129], v[190:193], v[110:113]
	v_mfma_i32_16x16x64_i8 v[106:109], v[134:137], v[190:193], v[106:109]
	v_mfma_i32_16x16x64_i8 v[94:97], v[126:129], v[198:201], v[94:97]
	v_mfma_i32_16x16x64_i8 v[90:93], v[134:137], v[198:201], v[90:93]
	v_mfma_i32_16x16x64_i8 v[78:81], v[126:129], v[206:209], v[78:81]
	v_mfma_i32_16x16x64_i8 v[74:77], v[134:137], v[206:209], v[74:77]
	s_setprio 0
	s_setprio 1
	v_mfma_i32_16x16x64_i8 v[118:121], v[162:165], v[178:181], v[118:121]
	v_mfma_i32_16x16x64_i8 v[114:117], v[170:173], v[178:181], v[114:117]
	v_mfma_i32_16x16x64_i8 v[102:105], v[162:165], v[186:189], v[102:105]
	v_mfma_i32_16x16x64_i8 v[98:101], v[170:173], v[186:189], v[98:101]
	v_mfma_i32_16x16x64_i8 v[86:89], v[162:165], v[194:197], v[86:89]
	v_mfma_i32_16x16x64_i8 v[82:85], v[170:173], v[194:197], v[82:85]
	v_mfma_i32_16x16x64_i8 v[70:73], v[162:165], v[202:205], v[70:73]
	v_mfma_i32_16x16x64_i8 v[66:69], v[170:173], v[202:205], v[66:69]
	v_mfma_i32_16x16x64_i8 v[118:121], v[166:169], v[182:185], v[118:121]
	v_mfma_i32_16x16x64_i8 v[114:117], v[174:177], v[182:185], v[114:117]
	v_mfma_i32_16x16x64_i8 v[102:105], v[166:169], v[190:193], v[102:105]
	v_mfma_i32_16x16x64_i8 v[98:101], v[174:177], v[190:193], v[98:101]
	v_mfma_i32_16x16x64_i8 v[86:89], v[166:169], v[198:201], v[86:89]
	v_mfma_i32_16x16x64_i8 v[82:85], v[174:177], v[198:201], v[82:85]
	v_mfma_i32_16x16x64_i8 v[70:73], v[166:169], v[206:209], v[70:73]
	v_mfma_i32_16x16x64_i8 v[66:69], v[174:177], v[206:209], v[66:69]
	s_setprio 0
	s_barrier
	s_mov_b32 m0, s44
	s_or_b32 s82, s80, 0x80
	ds_read_b128 v[178:181], v160 offset:49152
	ds_read_b128 v[182:185], v160 offset:50176
	ds_read_b128 v[186:189], v160 offset:51200
	ds_read_b128 v[190:193], v160 offset:52224
	ds_read_b128 v[194:197], v160 offset:53248
	ds_read_b128 v[198:201], v160 offset:54272
	ds_read_b128 v[202:205], v160 offset:55296
	ds_read_b128 v[206:209], v160 offset:56320
	buffer_load_dwordx4 v154, s[52:55], s82 offen lds
	s_mov_b32 m0, s45
	s_add_i32 s80, s80, 0x40080
	buffer_load_dwordx4 v156, s[52:55], s82 offen lds
	s_mov_b32 m0, s49
	s_nop 0
	buffer_load_dwordx4 v154, s[52:55], s80 offen lds
	s_mov_b32 m0, s51
	s_nop 0
	buffer_load_dwordx4 v156, s[52:55], s80 offen lds
	s_mov_b32 m0, s47
	s_nop 0
	buffer_load_dwordx4 v153, s[28:31], s79 offen lds
	s_mov_b32 m0, s48
	s_nop 0
	buffer_load_dwordx4 v155, s[28:31], s79 offen lds
	s_waitcnt vmcnt(8)
	s_waitcnt lgkmcnt(0)
	s_barrier
	s_setprio 1
	v_mfma_i32_16x16x64_i8 v[62:65], v[122:125], v[178:181], v[62:65]
	v_mfma_i32_16x16x64_i8 v[58:61], v[130:133], v[178:181], v[58:61]
	v_mfma_i32_16x16x64_i8 v[46:49], v[122:125], v[186:189], v[46:49]
	v_mfma_i32_16x16x64_i8 v[42:45], v[130:133], v[186:189], v[42:45]
	v_mfma_i32_16x16x64_i8 v[30:33], v[122:125], v[194:197], v[30:33]
	v_mfma_i32_16x16x64_i8 v[26:29], v[130:133], v[194:197], v[26:29]
	v_mfma_i32_16x16x64_i8 v[14:17], v[122:125], v[202:205], v[14:17]
	v_mfma_i32_16x16x64_i8 v[10:13], v[130:133], v[202:205], v[10:13]
	v_mfma_i32_16x16x64_i8 v[62:65], v[126:129], v[182:185], v[62:65]
	v_mfma_i32_16x16x64_i8 v[58:61], v[134:137], v[182:185], v[58:61]
	v_mfma_i32_16x16x64_i8 v[46:49], v[126:129], v[190:193], v[46:49]
	v_mfma_i32_16x16x64_i8 v[42:45], v[134:137], v[190:193], v[42:45]
	v_mfma_i32_16x16x64_i8 v[30:33], v[126:129], v[198:201], v[30:33]
	v_mfma_i32_16x16x64_i8 v[26:29], v[134:137], v[198:201], v[26:29]
	v_mfma_i32_16x16x64_i8 v[14:17], v[126:129], v[206:209], v[14:17]
	v_mfma_i32_16x16x64_i8 v[10:13], v[134:137], v[206:209], v[10:13]
	s_setprio 0
	s_setprio 1
	v_mfma_i32_16x16x64_i8 v[54:57], v[162:165], v[178:181], v[54:57]
	v_mfma_i32_16x16x64_i8 v[50:53], v[170:173], v[178:181], v[50:53]
	v_mfma_i32_16x16x64_i8 v[38:41], v[162:165], v[186:189], v[38:41]
	v_mfma_i32_16x16x64_i8 v[34:37], v[170:173], v[186:189], v[34:37]
	v_mfma_i32_16x16x64_i8 v[22:25], v[162:165], v[194:197], v[22:25]
	v_mfma_i32_16x16x64_i8 v[18:21], v[170:173], v[194:197], v[18:21]
	v_mfma_i32_16x16x64_i8 v[6:9], v[162:165], v[202:205], v[6:9]
	v_mfma_i32_16x16x64_i8 v[2:5], v[170:173], v[202:205], v[2:5]
	v_mfma_i32_16x16x64_i8 v[54:57], v[166:169], v[182:185], v[54:57]
	v_mfma_i32_16x16x64_i8 v[50:53], v[174:177], v[182:185], v[50:53]
	v_mfma_i32_16x16x64_i8 v[38:41], v[166:169], v[190:193], v[38:41]
	v_mfma_i32_16x16x64_i8 v[34:37], v[174:177], v[190:193], v[34:37]
	v_mfma_i32_16x16x64_i8 v[22:25], v[166:169], v[198:201], v[22:25]
	v_mfma_i32_16x16x64_i8 v[18:21], v[174:177], v[198:201], v[18:21]
	v_mfma_i32_16x16x64_i8 v[6:9], v[166:169], v[206:209], v[6:9]
	v_mfma_i32_16x16x64_i8 v[2:5], v[174:177], v[206:209], v[2:5]
	s_setprio 0
	s_barrier
	s_add_i32 s78, s78, 2
	s_addk_i32 s76, 0x100
	s_addk_i32 s77, 0x100
	s_cmp_gt_u32 s78, 13
	s_cbranch_scc0 .LBB0_844
	s_and_b64 vcc, exec, s[12:13]
	s_cbranch_vccz .LBB0_847
	s_barrier

.LBB0_1161:
	ds_read_b128 v[136:139], v203
	ds_read_b128 v[140:143], v203 offset:1024
	ds_read_b128 v[144:147], v203 offset:2048
	ds_read_b128 v[148:151], v203 offset:3072
	ds_read_b128 v[152:155], v204
	ds_read_b128 v[156:159], v204 offset:1024
	ds_read_b128 v[160:163], v204 offset:2048
	ds_read_b128 v[164:167], v204 offset:3072
	s_add_i32 s47, s67, 0xfff80080
	s_cmp_lg_u32 s79, 28
	s_cselect_b32 s88, s47, 0
	s_add_i32 s89, s88, s15
	s_or_b32 s80, s89, 0x80
	s_add_i32 s88, s88, s6
	s_add_i32 s59, s15, s67
	s_mov_b32 s47, s31
	s_mov_b32 m0, s77
	ds_read_b128 v[168:171], v135
	ds_read_b128 v[172:175], v135 offset:1024
	ds_read_b128 v[176:179], v135 offset:2048
	ds_read_b128 v[180:183], v135 offset:3072
	ds_read_b128 v[184:187], v135 offset:4096
	ds_read_b128 v[188:191], v135 offset:5120
	ds_read_b128 v[192:195], v135 offset:6144
	ds_read_b128 v[196:199], v135 offset:7168
	buffer_load_dwordx4 v130, s[44:47], s59 offen lds
	s_mov_b32 m0, s78
	s_nop 0
	buffer_load_dwordx4 v132, s[44:47], s59 offen lds
	s_waitcnt vmcnt(8)
	s_waitcnt lgkmcnt(0)
	s_barrier
	s_setprio 1
	v_mfma_f32_16x16x32_bf16 v[30:33], v[136:139], v[168:171], v[30:33]
	v_mfma_f32_16x16x32_bf16 v[26:29], v[144:147], v[168:171], v[26:29]
	v_mfma_f32_16x16x32_bf16 v[54:57], v[136:139], v[176:179], v[54:57]
	v_mfma_f32_16x16x32_bf16 v[50:53], v[144:147], v[176:179], v[50:53]
	v_mfma_f32_16x16x32_bf16 v[78:81], v[136:139], v[184:187], v[78:81]
	v_mfma_f32_16x16x32_bf16 v[74:77], v[144:147], v[184:187], v[74:77]
	v_mfma_f32_16x16x32_bf16 v[102:105], v[136:139], v[192:195], v[102:105]
	v_mfma_f32_16x16x32_bf16 v[94:97], v[144:147], v[192:195], v[94:97]
	v_mfma_f32_16x16x32_bf16 v[30:33], v[140:143], v[172:175], v[30:33]
	v_mfma_f32_16x16x32_bf16 v[26:29], v[148:151], v[172:175], v[26:29]
	v_mfma_f32_16x16x32_bf16 v[54:57], v[140:143], v[180:183], v[54:57]
	v_mfma_f32_16x16x32_bf16 v[50:53], v[148:151], v[180:183], v[50:53]
	v_mfma_f32_16x16x32_bf16 v[78:81], v[140:143], v[188:191], v[78:81]
	v_mfma_f32_16x16x32_bf16 v[74:77], v[148:151], v[188:191], v[74:77]
	v_mfma_f32_16x16x32_bf16 v[102:105], v[140:143], v[196:199], v[102:105]
	v_mfma_f32_16x16x32_bf16 v[94:97], v[148:151], v[196:199], v[94:97]
	s_setprio 0
	s_setprio 1
	v_mfma_f32_16x16x32_bf16 v[42:45], v[152:155], v[168:171], v[42:45]
	v_mfma_f32_16x16x32_bf16 v[34:37], v[160:163], v[168:171], v[34:37]
	v_mfma_f32_16x16x32_bf16 v[66:69], v[152:155], v[176:179], v[66:69]
	v_mfma_f32_16x16x32_bf16 v[58:61], v[160:163], v[176:179], v[58:61]
	v_mfma_f32_16x16x32_bf16 v[86:89], v[152:155], v[184:187], v[86:89]
	v_mfma_f32_16x16x32_bf16 v[82:85], v[160:163], v[184:187], v[82:85]
	v_mfma_f32_16x16x32_bf16 v[110:113], v[152:155], v[192:195], v[110:113]
	v_mfma_f32_16x16x32_bf16 v[106:109], v[160:163], v[192:195], v[106:109]
	v_mfma_f32_16x16x32_bf16 v[42:45], v[156:159], v[172:175], v[42:45]
	v_mfma_f32_16x16x32_bf16 v[34:37], v[164:167], v[172:175], v[34:37]
	v_mfma_f32_16x16x32_bf16 v[66:69], v[156:159], v[180:183], v[66:69]
	v_mfma_f32_16x16x32_bf16 v[58:61], v[164:167], v[180:183], v[58:61]
	v_mfma_f32_16x16x32_bf16 v[86:89], v[156:159], v[188:191], v[86:89]
	v_mfma_f32_16x16x32_bf16 v[82:85], v[164:167], v[188:191], v[82:85]
	v_mfma_f32_16x16x32_bf16 v[110:113], v[156:159], v[196:199], v[110:113]
	v_mfma_f32_16x16x32_bf16 v[106:109], v[164:167], v[196:199], v[106:109]
	s_setprio 0
	s_barrier
	s_mov_b32 m0, s8
	s_mov_b32 s59, s31
	ds_read_b128 v[168:171], v135 offset:16384
	ds_read_b128 v[172:175], v135 offset:17408
	ds_read_b128 v[176:179], v135 offset:18432
	ds_read_b128 v[180:183], v135 offset:19456
	ds_read_b128 v[184:187], v135 offset:20480
	ds_read_b128 v[188:191], v135 offset:21504
	ds_read_b128 v[192:195], v135 offset:22528
	ds_read_b128 v[196:199], v135 offset:23552
	buffer_load_dwordx4 v131, s[56:59], s88 offen lds
	s_mov_b32 m0, s9
	s_add_i32 s90, s88, 0x80000
	buffer_load_dwordx4 v133, s[56:59], s88 offen lds
	s_mov_b32 m0, s13
	s_nop 0
	buffer_load_dwordx4 v131, s[56:59], s90 offen lds
	s_mov_b32 m0, s14
	s_nop 0
	buffer_load_dwordx4 v133, s[56:59], s90 offen lds
	s_mov_b32 m0, s7
	s_nop 0
	buffer_load_dwordx4 v130, s[44:47], s89 offen lds
	s_mov_b32 m0, s16
	s_nop 0
	buffer_load_dwordx4 v132, s[44:47], s89 offen lds
	s_waitcnt vmcnt(8)
	s_waitcnt lgkmcnt(0)
	s_barrier
	s_setprio 1
	v_mfma_f32_16x16x32_bf16 v[126:129], v[136:139], v[168:171], v[126:129]
	v_mfma_f32_16x16x32_bf16 v[118:121], v[144:147], v[168:171], v[118:121]
	v_mfma_f32_16x16x32_bf16 v[98:101], v[136:139], v[176:179], v[98:101]
	v_mfma_f32_16x16x32_bf16 v[90:93], v[144:147], v[176:179], v[90:93]
	v_mfma_f32_16x16x32_bf16 v[46:49], v[136:139], v[184:187], v[46:49]
	v_mfma_f32_16x16x32_bf16 v[38:41], v[144:147], v[184:187], v[38:41]
	v_mfma_f32_16x16x32_bf16 v[14:17], v[136:139], v[192:195], v[14:17]
	v_mfma_f32_16x16x32_bf16 v[10:13], v[144:147], v[192:195], v[10:13]
	v_mfma_f32_16x16x32_bf16 v[126:129], v[140:143], v[172:175], v[126:129]
	v_mfma_f32_16x16x32_bf16 v[118:121], v[148:151], v[172:175], v[118:121]
	v_mfma_f32_16x16x32_bf16 v[98:101], v[140:143], v[180:183], v[98:101]
	v_mfma_f32_16x16x32_bf16 v[90:93], v[148:151], v[180:183], v[90:93]
	v_mfma_f32_16x16x32_bf16 v[46:49], v[140:143], v[188:191], v[46:49]
	v_mfma_f32_16x16x32_bf16 v[38:41], v[148:151], v[188:191], v[38:41]
	v_mfma_f32_16x16x32_bf16 v[14:17], v[140:143], v[196:199], v[14:17]
	v_mfma_f32_16x16x32_bf16 v[10:13], v[148:151], v[196:199], v[10:13]
	s_setprio 0
	s_setprio 1
	v_mfma_f32_16x16x32_bf16 v[122:125], v[152:155], v[168:171], v[122:125]
	v_mfma_f32_16x16x32_bf16 v[114:117], v[160:163], v[168:171], v[114:117]
	v_mfma_f32_16x16x32_bf16 v[70:73], v[152:155], v[176:179], v[70:73]
	v_mfma_f32_16x16x32_bf16 v[62:65], v[160:163], v[176:179], v[62:65]
	v_mfma_f32_16x16x32_bf16 v[22:25], v[152:155], v[184:187], v[22:25]
	v_mfma_f32_16x16x32_bf16 v[18:21], v[160:163], v[184:187], v[18:21]
	v_mfma_f32_16x16x32_bf16 v[6:9], v[152:155], v[192:195], v[6:9]
	v_mfma_f32_16x16x32_bf16 v[2:5], v[160:163], v[192:195], v[2:5]
	v_mfma_f32_16x16x32_bf16 v[122:125], v[156:159], v[172:175], v[122:125]
	v_mfma_f32_16x16x32_bf16 v[114:117], v[164:167], v[172:175], v[114:117]
	v_mfma_f32_16x16x32_bf16 v[70:73], v[156:159], v[180:183], v[70:73]
	v_mfma_f32_16x16x32_bf16 v[62:65], v[164:167], v[180:183], v[62:65]
	v_mfma_f32_16x16x32_bf16 v[22:25], v[156:159], v[188:191], v[22:25]
	v_mfma_f32_16x16x32_bf16 v[18:21], v[164:167], v[188:191], v[18:21]
	v_mfma_f32_16x16x32_bf16 v[6:9], v[156:159], v[196:199], v[6:9]
	v_mfma_f32_16x16x32_bf16 v[2:5], v[164:167], v[196:199], v[2:5]
	s_setprio 0
	s_barrier
	ds_read_b128 v[136:139], v205
	ds_read_b128 v[140:143], v205 offset:1024
	ds_read_b128 v[144:147], v205 offset:2048
	ds_read_b128 v[148:151], v205 offset:3072
	ds_read_b128 v[152:155], v206
	ds_read_b128 v[156:159], v206 offset:1024
	ds_read_b128 v[160:163], v206 offset:2048
	ds_read_b128 v[164:167], v206 offset:3072
	s_add_i32 s89, s89, 0x80000
	s_mov_b32 m0, s17
	ds_read_b128 v[168:171], v135 offset:32768
	ds_read_b128 v[172:175], v135 offset:33792
	ds_read_b128 v[176:179], v135 offset:34816
	ds_read_b128 v[180:183], v135 offset:35840
	ds_read_b128 v[184:187], v135 offset:36864
	ds_read_b128 v[188:191], v135 offset:37888
	ds_read_b128 v[192:195], v135 offset:38912
	ds_read_b128 v[196:199], v135 offset:39936
	buffer_load_dwordx4 v130, s[44:47], s89 offen lds
	s_mov_b32 m0, s18
	s_nop 0
	buffer_load_dwordx4 v132, s[44:47], s89 offen lds
	s_waitcnt vmcnt(8)
	s_waitcnt lgkmcnt(0)
	s_barrier
	s_setprio 1
	v_mfma_f32_16x16x32_bf16 v[30:33], v[136:139], v[168:171], v[30:33]
	v_mfma_f32_16x16x32_bf16 v[26:29], v[144:147], v[168:171], v[26:29]
	v_mfma_f32_16x16x32_bf16 v[54:57], v[136:139], v[176:179], v[54:57]
	v_mfma_f32_16x16x32_bf16 v[50:53], v[144:147], v[176:179], v[50:53]
	v_mfma_f32_16x16x32_bf16 v[78:81], v[136:139], v[184:187], v[78:81]
	v_mfma_f32_16x16x32_bf16 v[74:77], v[144:147], v[184:187], v[74:77]
	v_mfma_f32_16x16x32_bf16 v[102:105], v[136:139], v[192:195], v[102:105]
	v_mfma_f32_16x16x32_bf16 v[94:97], v[144:147], v[192:195], v[94:97]
	v_mfma_f32_16x16x32_bf16 v[30:33], v[140:143], v[172:175], v[30:33]
	v_mfma_f32_16x16x32_bf16 v[26:29], v[148:151], v[172:175], v[26:29]
	v_mfma_f32_16x16x32_bf16 v[54:57], v[140:143], v[180:183], v[54:57]
	v_mfma_f32_16x16x32_bf16 v[50:53], v[148:151], v[180:183], v[50:53]
	v_mfma_f32_16x16x32_bf16 v[78:81], v[140:143], v[188:191], v[78:81]
	v_mfma_f32_16x16x32_bf16 v[74:77], v[148:151], v[188:191], v[74:77]
	v_mfma_f32_16x16x32_bf16 v[102:105], v[140:143], v[196:199], v[102:105]
	v_mfma_f32_16x16x32_bf16 v[94:97], v[148:151], v[196:199], v[94:97]
	s_setprio 0
	s_setprio 1
	v_mfma_f32_16x16x32_bf16 v[42:45], v[152:155], v[168:171], v[42:45]
	v_mfma_f32_16x16x32_bf16 v[34:37], v[160:163], v[168:171], v[34:37]
	v_mfma_f32_16x16x32_bf16 v[66:69], v[152:155], v[176:179], v[66:69]
	v_mfma_f32_16x16x32_bf16 v[58:61], v[160:163], v[176:179], v[58:61]
	v_mfma_f32_16x16x32_bf16 v[86:89], v[152:155], v[184:187], v[86:89]
	v_mfma_f32_16x16x32_bf16 v[82:85], v[160:163], v[184:187], v[82:85]
	v_mfma_f32_16x16x32_bf16 v[110:113], v[152:155], v[192:195], v[110:113]
	v_mfma_f32_16x16x32_bf16 v[106:109], v[160:163], v[192:195], v[106:109]
	v_mfma_f32_16x16x32_bf16 v[42:45], v[156:159], v[172:175], v[42:45]
	v_mfma_f32_16x16x32_bf16 v[34:37], v[164:167], v[172:175], v[34:37]
	v_mfma_f32_16x16x32_bf16 v[66:69], v[156:159], v[180:183], v[66:69]
	v_mfma_f32_16x16x32_bf16 v[58:61], v[164:167], v[180:183], v[58:61]
	v_mfma_f32_16x16x32_bf16 v[86:89], v[156:159], v[188:191], v[86:89]
	v_mfma_f32_16x16x32_bf16 v[82:85], v[164:167], v[188:191], v[82:85]
	v_mfma_f32_16x16x32_bf16 v[110:113], v[156:159], v[196:199], v[110:113]
	v_mfma_f32_16x16x32_bf16 v[106:109], v[164:167], v[196:199], v[106:109]
	s_setprio 0
	s_barrier
	s_mov_b32 m0, s19
	s_or_b32 s89, s88, 0x80
	ds_read_b128 v[168:171], v135 offset:49152
	ds_read_b128 v[172:175], v135 offset:50176
	ds_read_b128 v[176:179], v135 offset:51200
	ds_read_b128 v[180:183], v135 offset:52224
	ds_read_b128 v[184:187], v135 offset:53248
	ds_read_b128 v[188:191], v135 offset:54272
	ds_read_b128 v[192:195], v135 offset:55296
	ds_read_b128 v[196:199], v135 offset:56320
	buffer_load_dwordx4 v131, s[56:59], s89 offen lds
	s_mov_b32 m0, s52
	s_add_i32 s88, s88, 0x80080
	buffer_load_dwordx4 v133, s[56:59], s89 offen lds
	s_mov_b32 m0, s65
	s_nop 0
	buffer_load_dwordx4 v131, s[56:59], s88 offen lds
	s_mov_b32 m0, s76
	s_nop 0
	buffer_load_dwordx4 v133, s[56:59], s88 offen lds
	s_mov_b32 m0, s53
	s_nop 0
	buffer_load_dwordx4 v130, s[44:47], s80 offen lds
	s_mov_b32 m0, s64
	s_nop 0
	buffer_load_dwordx4 v132, s[44:47], s80 offen lds
	s_waitcnt vmcnt(8)
	s_waitcnt lgkmcnt(0)
	s_barrier
	s_setprio 1
	v_mfma_f32_16x16x32_bf16 v[126:129], v[136:139], v[168:171], v[126:129]
	v_mfma_f32_16x16x32_bf16 v[118:121], v[144:147], v[168:171], v[118:121]
	v_mfma_f32_16x16x32_bf16 v[98:101], v[136:139], v[176:179], v[98:101]
	v_mfma_f32_16x16x32_bf16 v[90:93], v[144:147], v[176:179], v[90:93]
	v_mfma_f32_16x16x32_bf16 v[46:49], v[136:139], v[184:187], v[46:49]
	v_mfma_f32_16x16x32_bf16 v[38:41], v[144:147], v[184:187], v[38:41]
	v_mfma_f32_16x16x32_bf16 v[14:17], v[136:139], v[192:195], v[14:17]
	v_mfma_f32_16x16x32_bf16 v[10:13], v[144:147], v[192:195], v[10:13]
	v_mfma_f32_16x16x32_bf16 v[126:129], v[140:143], v[172:175], v[126:129]
	v_mfma_f32_16x16x32_bf16 v[118:121], v[148:151], v[172:175], v[118:121]
	v_mfma_f32_16x16x32_bf16 v[98:101], v[140:143], v[180:183], v[98:101]
	v_mfma_f32_16x16x32_bf16 v[90:93], v[148:151], v[180:183], v[90:93]
	v_mfma_f32_16x16x32_bf16 v[46:49], v[140:143], v[188:191], v[46:49]
	v_mfma_f32_16x16x32_bf16 v[38:41], v[148:151], v[188:191], v[38:41]
	v_mfma_f32_16x16x32_bf16 v[14:17], v[140:143], v[196:199], v[14:17]
	v_mfma_f32_16x16x32_bf16 v[10:13], v[148:151], v[196:199], v[10:13]
	s_setprio 0
	s_setprio 1
	v_mfma_f32_16x16x32_bf16 v[122:125], v[152:155], v[168:171], v[122:125]
	v_mfma_f32_16x16x32_bf16 v[114:117], v[160:163], v[168:171], v[114:117]
	v_mfma_f32_16x16x32_bf16 v[70:73], v[152:155], v[176:179], v[70:73]
	v_mfma_f32_16x16x32_bf16 v[62:65], v[160:163], v[176:179], v[62:65]
	v_mfma_f32_16x16x32_bf16 v[22:25], v[152:155], v[184:187], v[22:25]
	v_mfma_f32_16x16x32_bf16 v[18:21], v[160:163], v[184:187], v[18:21]
	v_mfma_f32_16x16x32_bf16 v[6:9], v[152:155], v[192:195], v[6:9]
	v_mfma_f32_16x16x32_bf16 v[2:5], v[160:163], v[192:195], v[2:5]
	v_mfma_f32_16x16x32_bf16 v[122:125], v[156:159], v[172:175], v[122:125]
	v_mfma_f32_16x16x32_bf16 v[114:117], v[164:167], v[172:175], v[114:117]
	v_mfma_f32_16x16x32_bf16 v[70:73], v[156:159], v[180:183], v[70:73]
	v_mfma_f32_16x16x32_bf16 v[62:65], v[164:167], v[180:183], v[62:65]
	v_mfma_f32_16x16x32_bf16 v[22:25], v[156:159], v[188:191], v[22:25]
	v_mfma_f32_16x16x32_bf16 v[18:21], v[164:167], v[188:191], v[18:21]
	v_mfma_f32_16x16x32_bf16 v[6:9], v[156:159], v[196:199], v[6:9]
	v_mfma_f32_16x16x32_bf16 v[2:5], v[164:167], v[196:199], v[2:5]
	s_setprio 0
	s_barrier
	s_add_i32 s79, s79, 2
	s_addk_i32 s67, 0x100
	s_cmp_lt_u32 s79, 30
	s_cbranch_scc1 .LBB0_1161
	s_waitcnt vmcnt(0)
	s_cmpk_gt_u32 s66, 0xff
	s_cbranch_scc1 .LBB0_1164
	s_barrier
